# chunkB loop: all next-chunk loads issued in the first part of the step (P/Rh blocks staged via LDS), none late before the end-of-step wait
# speedup vs baseline: 1.0132x; 1.0132x over previous
; __device__ __forceinline__ void chunkB_item(const Args& A, LAS unsigned char* lds, int tid, int lane, int wave, int bh) {
;     ...
;     bf16x8 p0[2][2], p1[2][2]; f32x4 q0[2], q1[2];
;     bf16x8 r0_[2][2], r1_[2][2]; u32x2 ya0[2], ya1[2], zc0[2], zc1[2], zp0[2], zp1[2], zg0[2], zg1[2]; float bc0[2], bc1[2];
;     B_LOAD(p0, q0, 0); B_LOADY(r0_, ya0, zc0, zp0, zg0, bc0, 0);
; #pragma unroll 1
;     for (int c = 0; c < 32; ++c) {
;         const int cn = c + 1 < 32 ? c + 1 : 31;
;         B_LOAD(p1, q1, cn); B_LOADY(r1_, ya1, zc1, zp1, zg1, bc1, cn);
;         B_STEP(p0, q0, r0_, ya0, zc0, zp0, zg0, bc0, c);
; #pragma unroll
;         for (int nn = 0; nn < 2; ++nn) { p0[nn][0] = p1[nn][0]; p0[nn][1] = p1[nn][1]; q0[nn] = q1[nn]; r0_[nn][0] = r1_[nn][0]; r0_[nn][1] = r1_[nn][1];
;             ya0[nn] = ya1[nn]; zc0[nn] = zc1[nn]; zp0[nn] = zp1[nn]; zg0[nn] = zg1[nn]; bc0[nn] = bc1[nn]; }
.LBB0_279:
	s_or_b64 exec, exec, s[22:23]
	s_waitcnt lgkmcnt(0)
	s_barrier
	v_mov_b32_dpp v170, v174 row_shr:1 row_mask:0xf bank_mask:0xf
	v_mov_b32_dpp v171, v175 row_shr:1 row_mask:0xf bank_mask:0xf
	v_mov_b32_dpp v164, v174 row_ror:1 row_mask:0xf bank_mask:0xf
	v_mov_b32_dpp v165, v175 row_ror:1 row_mask:0xf bank_mask:0xf
	v_mov_b32_dpp v164, v168 row_shr:1 row_mask:0xf bank_mask:0xf
	v_mov_b32_dpp v165, v169 row_shr:1 row_mask:0xf bank_mask:0xf
	ds_read2st64_b64 v[20:23], v141 offset0:36 offset1:37
	s_waitcnt lgkmcnt(1)
	ds_read2st64_b64 v[36:39], v141 offset0:38 offset1:39
	v_lshlrev_b32_e32 v42, 16, v176
	v_and_b32_e32 v43, 0xffff0000, v176
	v_lshlrev_b32_e32 v40, 16, v174
	s_waitcnt lgkmcnt(1)
	v_pk_add_f32 v[20:21], v[20:21], 0 op_sel_hi:[1,0]
	v_and_b32_e32 v41, 0xffff0000, v174
	v_pk_add_f32 v[20:21], v[20:21], v[22:23]
	v_mul_f32_e32 v23, 0xbfb8aa3b, v42
	s_waitcnt lgkmcnt(0)
	v_pk_add_f32 v[20:21], v[20:21], v[36:37]
	v_exp_f32_e32 v23, v23
	v_pk_add_f32 v[20:21], v[20:21], v[38:39]
	v_lshlrev_b32_e32 v36, 16, v170
	v_pk_mul_f32 v[20:21], v[20:21], s[10:11] op_sel_hi:[1,0]
	v_add_f32_e32 v23, 1.0, v23
	v_fma_f32 v22, -v20, v20, v21
	v_max_f32_e32 v22, 0, v22
	v_add_f32_e32 v22, 0x3a27c5ac, v22
	v_rcp_f32_e32 v38, v23
	v_mul_f32_e32 v23, 0xbfb8aa3b, v43
	v_rsq_f32_e32 v22, v22
	v_exp_f32_e32 v23, v23
	v_and_b32_e32 v37, 0xffff0000, v170
	v_pk_add_f32 v[56:57], v[198:199], v[20:21] op_sel_hi:[1,0] neg_lo:[0,1] neg_hi:[0,1]
	v_pk_add_f32 v[36:37], v[36:37], v[40:41] neg_lo:[0,1] neg_hi:[0,1]
	v_pk_mul_f32 v[56:57], v[56:57], v[22:23] op_sel_hi:[1,0]
	v_add_f32_e32 v23, 1.0, v23
	s_waitcnt vmcnt(13)
	v_pk_fma_f32 v[36:37], v[36:37], v[232:233], v[40:41]
	v_lshlrev_b32_e32 v40, 16, v177
	v_rcp_f32_e32 v39, v23
	v_mul_f32_e32 v23, 0xbfb8aa3b, v40
	v_exp_f32_e32 v23, v23
	v_pk_fma_f32 v[56:57], v[228:229], v[56:57], v[250:251]
	v_and_b32_e32 v41, 0xffff0000, v177
	v_pk_fma_f32 v[36:37], v[172:173], v[36:37], v[56:57] op_sel_hi:[0,1,1]
	v_add_f32_e32 v23, 1.0, v23
	v_rcp_f32_e32 v56, v23
	v_mul_f32_e32 v23, 0xbfb8aa3b, v41
	v_exp_f32_e32 v23, v23
	v_pk_add_f32 v[20:21], v[196:197], v[20:21] op_sel_hi:[1,0] neg_lo:[0,1] neg_hi:[0,1]
	v_pk_mul_f32 v[38:39], v[38:39], v[42:43]
	v_lshlrev_b32_e32 v42, 16, v171
	v_pk_mul_f32 v[20:21], v[20:21], v[22:23] op_sel_hi:[1,0]
	v_add_f32_e32 v22, 1.0, v23
	v_rcp_f32_e32 v57, v22
	v_pk_mul_f32 v[36:37], v[38:39], v[36:37]
	v_lshlrev_b32_e32 v38, 16, v175
	v_and_b32_e32 v39, 0xffff0000, v175
	v_and_b32_e32 v43, 0xffff0000, v171
	v_pk_add_f32 v[22:23], v[42:43], v[38:39] neg_lo:[0,1] neg_hi:[0,1]
	v_pk_fma_f32 v[20:21], v[230:231], v[20:21], v[252:253]
	v_pk_fma_f32 v[22:23], v[22:23], v[254:255], v[38:39]
	v_lshl_add_u64 v[42:43], v[160:161], 0, s[20:21]
	v_pk_fma_f32 v[20:21], v[172:173], v[22:23], v[20:21] op_sel_hi:[0,1,1]
	v_pk_mul_f32 v[22:23], v[56:57], v[40:41]
	v_cvt_pk_bf16_f32 v40, v36, v37
	v_pk_mul_f32 v[38:39], v[22:23], v[20:21]
	ds_read2st64_b64 v[20:23], v143 offset0:36 offset1:37
	v_cvt_pk_bf16_f32 v41, v38, v39
	ds_read2st64_b64 v[36:39], v143 offset0:38 offset1:39
	global_store_dwordx2 v[42:43], v[40:41], off
	v_lshlrev_b32_e32 v40, 16, v164
	s_waitcnt lgkmcnt(1)
	v_pk_add_f32 v[20:21], v[20:21], 0 op_sel_hi:[1,0]
	v_and_b32_e32 v41, 0xffff0000, v164
	v_pk_add_f32 v[20:21], v[20:21], v[22:23]
	s_waitcnt lgkmcnt(0)
	v_pk_add_f32 v[20:21], v[20:21], v[36:37]
	v_lshlrev_b32_e32 v36, 16, v168
	v_pk_add_f32 v[20:21], v[20:21], v[38:39]
	v_lshlrev_b32_e32 v38, 16, v166
	v_mul_f32_e32 v23, 0xbfb8aa3b, v38
	v_exp_f32_e32 v23, v23
	v_pk_mul_f32 v[20:21], v[20:21], s[10:11] op_sel_hi:[1,0]
	v_and_b32_e32 v39, 0xffff0000, v166
	v_fma_f32 v22, -v20, v20, v21
	v_max_f32_e32 v22, 0, v22
	v_add_f32_e32 v23, 1.0, v23
	v_add_f32_e32 v22, 0x3a27c5ac, v22
	v_rcp_f32_e32 v42, v23
	v_mul_f32_e32 v23, 0xbfb8aa3b, v39
	v_rsq_f32_e32 v22, v22
	v_exp_f32_e32 v23, v23
	v_and_b32_e32 v37, 0xffff0000, v168
	v_pk_add_f32 v[54:55], v[54:55], v[20:21] op_sel_hi:[1,0] neg_lo:[0,1] neg_hi:[0,1]
	v_pk_add_f32 v[40:41], v[40:41], v[36:37] neg_lo:[0,1] neg_hi:[0,1]
	v_pk_mul_f32 v[54:55], v[54:55], v[22:23] op_sel_hi:[1,0]
	v_add_f32_e32 v23, 1.0, v23
	v_pk_fma_f32 v[36:37], v[40:41], v[232:233], v[36:37]
	v_lshlrev_b32_e32 v40, 16, v167
	v_rcp_f32_e32 v43, v23
	v_mul_f32_e32 v23, 0xbfb8aa3b, v40
	v_exp_f32_e32 v23, v23
	v_pk_fma_f32 v[54:55], v[228:229], v[54:55], v[250:251]
	v_and_b32_e32 v41, 0xffff0000, v167
	v_pk_fma_f32 v[36:37], v[162:163], v[36:37], v[54:55] op_sel_hi:[0,1,1]
	v_add_f32_e32 v23, 1.0, v23
	v_rcp_f32_e32 v54, v23
	v_mul_f32_e32 v23, 0xbfb8aa3b, v41
	v_exp_f32_e32 v23, v23
	v_pk_add_f32 v[20:21], v[52:53], v[20:21] op_sel_hi:[1,0] neg_lo:[0,1] neg_hi:[0,1]
	v_pk_mul_f32 v[38:39], v[42:43], v[38:39]
	v_lshlrev_b32_e32 v42, 16, v165
	v_pk_mul_f32 v[20:21], v[20:21], v[22:23] op_sel_hi:[1,0]
	v_add_f32_e32 v22, 1.0, v23
	v_rcp_f32_e32 v55, v22
	v_pk_mul_f32 v[36:37], v[38:39], v[36:37]
	v_lshlrev_b32_e32 v38, 16, v169
	v_and_b32_e32 v39, 0xffff0000, v169
	v_and_b32_e32 v43, 0xffff0000, v165
	v_pk_add_f32 v[22:23], v[42:43], v[38:39] neg_lo:[0,1] neg_hi:[0,1]
	v_pk_fma_f32 v[20:21], v[230:231], v[20:21], v[252:253]
	v_pk_fma_f32 v[22:23], v[22:23], v[254:255], v[38:39]
	v_pk_fma_f32 v[20:21], v[162:163], v[22:23], v[20:21] op_sel_hi:[0,1,1]
	v_pk_mul_f32 v[22:23], v[54:55], v[40:41]
	v_pk_mul_f32 v[20:21], v[22:23], v[20:21]
	v_cvt_pk_bf16_f32 v22, v36, v37
	v_cvt_pk_bf16_f32 v23, v20, v21
	v_lshl_add_u64 v[20:21], v[158:159], 0, s[20:21]
	s_add_u32 s20, s20, 0x20000
	global_store_dwordx2 v[20:21], v[22:23], off
	s_addc_u32 s21, s21, 0
	s_add_i32 s39, s39, 1
	s_waitcnt vmcnt(2)
	v_mov_b64_e32 v[164:165], v[192:193]
	s_cmp_eq_u32 s20, 0x400000
	v_mov_b64_e32 v[170:171], v[186:187]
	v_mov_b64_e32 v[166:167], v[190:191]
	v_mov_b64_e32 v[176:177], v[184:185]
	v_mov_b64_e32 v[174:175], v[182:183]
	v_mov_b64_e32 v[168:169], v[188:189]
	v_mov_b32_e32 v162, v127
	v_mov_b32_e32 v172, v125
	v_mov_b32_e32 v40, v216
	v_mov_b32_e32 v41, v217
	v_mov_b32_e32 v42, v218
	v_mov_b32_e32 v43, v219
	v_mov_b32_e32 v196, v178
	v_mov_b32_e32 v197, v179
	v_mov_b32_e32 v194, v180
	v_mov_b32_e32 v195, v181
	s_cbranch_scc1 .LBB0_268
.LBB0_280:
	s_cmp_lg_u32 s20, 0x3e0000
	s_cselect_b32 s15, s39, 31
	s_add_u32 s22, s18, s15
	s_addc_u32 s23, s19, 0
	s_mul_i32 s40, s23, 0x6000
	s_mul_hi_u32 s41, s22, 0x6000
	s_add_i32 s41, s41, s40
	s_mul_i32 s40, s22, 0x6000
	s_add_u32 s40, s86, s40
	s_addc_u32 s41, s87, s41
	s_waitcnt vmcnt(10)
	ds_write_b128 v246, v[0:3] offset:43008
	ds_write_b128 v246, v[8:11] offset:51200
	ds_write_b64 v242, v[182:183]
	ds_write_b64 v242, v[188:189] offset:576
	ds_write_b64 v242, v[184:185] offset:9216
	ds_write_b64 v242, v[190:191] offset:9792
	s_lshl_b64 s[100:101], s[22:23], 14
	s_add_u32 s100, s3, s100
	s_addc_u32 s101, s11, s101
	s_lshl_b64 s[22:23], s[22:23], 8
	s_add_u32 s22, s24, s22
	s_addc_u32 s23, s25, s23
	s_lshl_b32 s15, s15, 6
	s_waitcnt vmcnt(10)
	s_add_u32 s15, s16, s15
	v_mov_b32_e32 v76, v210
	v_mov_b32_e32 v77, v211
	v_mov_b32_e32 v78, v212
	v_mov_b32_e32 v79, v213
	s_sub_u32 s98, s15, 1
	s_mul_i32 s98, s98, 0x1c00
	s_add_u32 s98, s98, s94
	s_addc_u32 s99, s95, 0
	s_mov_b32 vcc_lo, 0x10001
	s_mov_b32 vcc_hi, 0x10001
	global_load_dwordx2 v[182:183], v240, s[98:99]
	global_load_dwordx2 v[188:189], v241, s[98:99]
	global_load_dwordx2 v[184:185], v240, s[98:99] offset:1280
	global_load_dwordx2 v[190:191], v241, s[98:99] offset:1280
	s_mov_b64 exec, vcc
	global_load_dwordx2 v[186:187], v245, s[98:99]
	s_mov_b64 exec, -1
	global_load_dword v125, v214, s[22:23]
	global_load_dword v127, v215, s[22:23]
	v_cvt_pk_bf16_f32 v80, v16, 0
	v_lshlrev_b32_e32 v81, 16, v80
	v_sub_f32_e32 v16, v16, v81
	v_cvt_pk_bf16_f32 v16, v16, s0
	ds_write_b16 v107, v80
	ds_write_b16 v107, v16 offset:9216
	v_cvt_pk_bf16_f32 v16, v17, 0
	v_lshlrev_b32_e32 v80, 16, v16
	v_sub_f32_e32 v17, v17, v80
	v_cvt_pk_bf16_f32 v17, v17, s0
	ds_write_b16 v107, v16 offset:144
	ds_write_b16 v107, v17 offset:9360
	v_cvt_pk_bf16_f32 v16, v18, 0
	v_lshlrev_b32_e32 v17, 16, v16
	v_sub_f32_e32 v17, v18, v17
	v_cvt_pk_bf16_f32 v17, v17, s0
	ds_write_b16 v107, v16 offset:288
	ds_write_b16 v107, v17 offset:9504
	v_cvt_pk_bf16_f32 v16, v19, 0
	v_lshlrev_b32_e32 v17, 16, v16
	v_sub_f32_e32 v17, v19, v17
	v_cvt_pk_bf16_f32 v17, v17, s0
	ds_write_b16 v107, v16 offset:432
	ds_write_b16 v107, v17 offset:9648
	v_cvt_pk_bf16_f32 v16, v32, 0
	v_lshlrev_b32_e32 v17, 16, v16
	v_sub_f32_e32 v17, v32, v17
	v_cvt_pk_bf16_f32 v17, v17, s0
	ds_write_b16 v135, v16
	ds_write_b16 v135, v17 offset:9216
	v_cvt_pk_bf16_f32 v16, v33, 0
	v_lshlrev_b32_e32 v17, 16, v16
	v_sub_f32_e32 v17, v33, v17
	v_cvt_pk_bf16_f32 v17, v17, s0
	ds_write_b16 v135, v16 offset:144
	ds_write_b16 v135, v17 offset:9360
	v_cvt_pk_bf16_f32 v16, v34, 0
	v_lshlrev_b32_e32 v17, 16, v16
	v_sub_f32_e32 v17, v34, v17
	v_cvt_pk_bf16_f32 v17, v17, s0
	ds_write_b16 v135, v16 offset:288
	ds_write_b16 v135, v17 offset:9504
	v_cvt_pk_bf16_f32 v16, v35, 0
	v_lshlrev_b32_e32 v17, 16, v16
	v_sub_f32_e32 v17, v35, v17
	v_cvt_pk_bf16_f32 v17, v17, s0
	ds_write_b16 v135, v16 offset:432
	ds_write_b16 v135, v17 offset:9648
	s_waitcnt lgkmcnt(0)
	s_barrier
	ds_read_b128 v[198:201], v247 offset:43008
	ds_read_b128 v[224:227], v247 offset:51200
	ds_read_b128 v[72:75], v247 offset:44032
	ds_read_b128 v[220:223], v247 offset:52224
	ds_read_b128 v[36:39], v247 offset:45056
	ds_read_b128 v[20:23], v247 offset:46080
	ds_read_b128 v[56:59], v247 offset:53248
	ds_read_b128 v[52:55], v247 offset:54272
	ds_read_b128 v[80:83], v139
	ds_read_b128 v[32:35], v139 offset:64
	s_waitcnt lgkmcnt(1)
	v_mfma_f32_16x16x32_bf16 v[16:19], v[80:83], v[198:201], v[76:79]
	ds_read_b128 v[84:87], v139 offset:9216
	s_nop 1
	ds_read_b128 v[76:79], v139 offset:9280
	s_waitcnt vmcnt(7)
	v_lshlrev_b32_e32 v202, 16, v196
	v_and_b32_e32 v203, 0xffff0000, v196
	s_waitcnt lgkmcnt(1)
	v_mfma_f32_16x16x32_bf16 v[16:19], v[84:87], v[198:201], v[16:19]
	v_lshlrev_b32_e32 v196, 16, v197
	v_and_b32_e32 v197, 0xffff0000, v197
	v_and_b32_e32 v151, 64, v209
	v_mfma_f32_16x16x32_bf16 v[198:201], v[80:83], v[224:227], 0
	v_xor_b32_e32 v149, 16, v209
	v_add_u32_e32 v151, 64, v151
	v_cmp_lt_i32_e32 vcc, v149, v151
	v_mfma_f32_16x16x32_bf16 v[198:201], v[32:35], v[220:223], v[198:201]
	v_xor_b32_e32 v224, 32, v209
	v_cndmask_b32_e32 v149, v209, v149, vcc
	v_lshlrev_b32_e32 v149, 2, v149
	v_cmp_lt_i32_e32 vcc, v224, v151
	v_mfma_f32_16x16x32_bf16 v[16:19], v[32:35], v[72:75], v[16:19]
	global_load_dwordx4 v[0:3], v246, s[40:41]
	s_nop 2
	v_add_f32_e64 v198, v198, v202
	v_add_f32_e64 v199, v199, v203
	v_pk_add_f32 v[196:197], v[200:201], v[196:197]
	v_pk_mul_f32 v[200:201], v[198:199], v[198:199]
	v_pk_mul_f32 v[202:203], v[196:197], v[196:197]
	global_load_dwordx4 v[8:11], v246, s[100:101]
	v_mov_b32_e32 v220, v198
	v_mov_b32_e32 v221, v200
	v_mov_b32_e32 v200, v199
	v_pk_add_f32 v[200:201], v[220:221], v[200:201]
	v_mov_b32_e32 v220, v196
	v_mov_b32_e32 v221, v202
	v_mov_b32_e32 v202, v197
	v_pk_add_f32 v[202:203], v[220:221], v[202:203]
	v_cndmask_b32_e32 v151, v209, v224, vcc
	global_load_dwordx4 v[210:213], v236, s[40:41]
	v_pk_add_f32 v[200:201], v[200:201], v[202:203]
	ds_bpermute_b32 v202, v149, v200
	ds_bpermute_b32 v203, v149, v201
	v_lshlrev_b32_e32 v151, 2, v151
	global_load_dwordx4 v[216:219], v237, s[40:41]
	global_load_dwordx2 v[178:179], v238, s[100:101]
	global_load_dwordx2 v[180:181], v239, s[100:101]
	s_waitcnt lgkmcnt(2)
	v_mfma_f32_16x16x32_bf16 v[16:19], v[76:79], v[72:75], v[16:19]
	s_waitcnt lgkmcnt(0)
	v_pk_add_f32 v[200:201], v[200:201], v[202:203]
	ds_bpermute_b32 v202, v151, v200
	ds_bpermute_b32 v203, v151, v201
	s_and_saveexec_b64 s[22:23], s[30:31]
	s_cbranch_execz .LBB0_282
	s_waitcnt lgkmcnt(0)
	v_pk_add_f32 v[72:73], v[200:201], v[202:203]
	v_add_u32_e32 v74, s26, v130
	ds_write_b64 v74, v[72:73] offset:18432
